# conv rewrite inline, insertion padded to 2560 B so later code keeps its 256-B alignment
# speedup vs baseline: 1.0040x; 1.0040x over previous
; #define LAS __attribute__((address_space(3)))
; DI unsigned xb_xcc_id() { return (unsigned)__builtin_amdgcn_s_getreg((3 << 11) | 20) & 0xFu; }
; __global__ void __launch_bounds__(512) fwd_megakernel(Params P) {
;     ...
;     for (int ph = P.ph_lo; ph < P.ph_hi; ++ph) {
;         run_phase(P, ph, smem);
;         if (ph + 1 < P.ph_hi) {
;             if (ph == P.ph_lo) { cg::this_grid().sync(); (void)xcd_barrier_post((unsigned*)(P.ws + OFF_BAR), (volatile LAS unsigned*)(smem + LDS_XB)); }
;             else { XcdBarrier xb; xb.bar = (unsigned*)(P.ws + OFF_BAR); xb.x = xb_xcc_id(); xb.st = (volatile LAS unsigned*)(smem + LDS_XB); xcd_barrier(xb); }
;         }
;     }
.Lhop15:
	s_branch .LBB0_15
	s_nop 0
	s_nop 0
	s_nop 0
	s_nop 0
	s_nop 0
	s_nop 0
	s_nop 0
	s_nop 0
	s_nop 0
	s_nop 0
	s_nop 0
	s_nop 0
	s_nop 0
	s_nop 0
	s_nop 0
	s_nop 0
	s_nop 0
	s_nop 0
	s_nop 0
	s_nop 0
	s_nop 0
	s_nop 0
	s_nop 0
	s_nop 0
	s_nop 0
	s_nop 0
	s_nop 0
	s_nop 0
	s_nop 0
	s_nop 0
	s_nop 0
	s_nop 0
	s_nop 0
	s_nop 0
	s_nop 0
	s_nop 0
	s_nop 0
	s_nop 0
	s_nop 0
	s_nop 0
	s_nop 0
	s_nop 0
	s_nop 0
	s_nop 0
	s_nop 0
	s_nop 0
	s_nop 0
	s_nop 0
	s_nop 0
